# diff-attn main loop: ALiBi C-operand constants kept in persistent VGPRs (no per-step LDS broadcast reads), QK MFMAs take them as SrcC
# speedup vs baseline: 1.0034x; 1.0034x over previous
; DI void diff_unit(unsigned char* smem, const bf16* __restrict__ QKV, bf16* __restrict__ Y, int h, int qb, float lam, float outscale, const float* __restrict__ gain, float kn0, float kn1, int tid) {
;     ...
;     if (tid < 3) flag[tid] = 0u;
;     if (tid < 32) ((volatile float*)(smem + D3_CI))[tid] = s8 * (float)(32 * (tid >> 4) + (tid & 3) + 8 * ((tid & 15) >> 2));
;     ...
;                 if (j < qb) {
; #pragma unroll
;                     for (int kh = 0; kh < 2; ++kh) { int cio = D3_CI + kh * 64; asm volatile("" : "+v"(cio)); p[kh] = *(const f32x16*)(smem + cio); }
.LBB0_201:
	s_or_b64 exec, exec, s[10:11]
	s_lshl_b32 s10, s61, 6
	s_or_b32 s10, s10, s42
	s_addk_i32 s10, 0xc1
	v_mov_b32_e32 v153, v152
	v_xor_b32_e32 v32, 64, v86
	v_xor_b32_e32 v188, 0x80, v86
	v_xor_b32_e32 v189, 0xc0, v86
	v_add_u32_e32 v190, s10, v84
	s_add_i32 s64, 0, 0x20044
	s_mov_b32 s65, 2
	s_mov_b32 s66, 0
	v_sub_u32_e32 v191, 0, v165
	s_mov_b32 s67, 1
	s_mov_b32 s68, 0x10000
	s_mov_b64 s[42:43], 0
	v_readlane_b32 s76, v252, 45
	v_readlane_b32 s80, v252, 47
	v_mov_b32_e32 v219, 0x20080
	ds_read_b128 v[220:223], v219
	ds_read_b128 v[224:227], v219 offset:16
	ds_read_b128 v[228:231], v219 offset:32
	ds_read_b128 v[232:235], v219 offset:48
	ds_read_b128 v[236:239], v219 offset:64
	ds_read_b128 v[240:243], v219 offset:80
	ds_read_b128 v[244:247], v219 offset:96
	ds_read_b128 v[248:251], v219 offset:112
	s_branch .LBB0_204

; #define MFMA32(a, b, c) __builtin_amdgcn_mfma_f32_32x32x16_bf16((a), (b), (c), 0, 0, 0)
; DI void diff_unit(unsigned char* smem, const bf16* __restrict__ QKV, bf16* __restrict__ Y, int h, int qb, float lam, float outscale, const float* __restrict__ gain, float kn0, float kn1, int tid) {
;     ...
;                     for (int ds = 0; ds < 4; ++ds) kf[kh * 4 + ds] = *(const bf16x8*)(tb + koff[ds] + kh * 8192);
;                 if (j < qb) {
; #pragma unroll
;                     for (int kh = 0; kh < 2; ++kh) { int cio = D3_CI + kh * 64; asm volatile("" : "+v"(cio)); p[kh] = *(const f32x16*)(smem + cio); }
;                 } else {
; #pragma unroll
;                     for (int kh = 0; kh < 2; ++kh)
; #pragma unroll
;                         for (int r = 0; r < 16; ++r) p[kh][r] = 0.f;
;                 }
;                 __builtin_amdgcn_sched_barrier(0);
; #pragma unroll
;                 for (int ds = 0; ds < 4; ++ds)
; #pragma unroll
;                     for (int kh = 0; kh < 2; ++kh) p[kh] = MFMA32(kf[kh * 4 + ds], qf[ds], p[kh]);
.Lmy_dma_top_skip:
	v_cmp_lt_i32_e32 vcc, 1, v85
	s_xor_b64 s[16:17], s[38:39], -1
	s_and_b64 s[56:57], vcc, s[16:17]
	s_mov_b64 s[16:17], s[38:39]
	s_and_saveexec_b64 s[54:55], s[56:57]
	s_cbranch_execz .Lmy_dma_stub
	s_add_i32 s81, s45, 0
	v_add_u32_e32 v34, s81, v167
	v_add_u32_e32 v35, s81, v168
	v_add_u32_e32 v36, s81, v169
	v_add_u32_e32 v37, s81, v186
	ds_read_b128 v[140:143], v34
	ds_read_b128 v[144:147], v34 offset:8192
	ds_read_b128 v[136:139], v35
	ds_read_b128 v[132:135], v35 offset:8192
	ds_read_b128 v[128:131], v36
	ds_read_b128 v[42:45], v36 offset:8192
	ds_read_b128 v[38:41], v37
	ds_read_b128 v[34:37], v37 offset:8192
	v_cmp_ge_i32_e32 vcc, v192, v166
	v_cmp_lt_i32_e64 s[16:17], v192, v166
	s_nop 0
	s_cmp_eq_u64 s[16:17], exec
	s_cbranch_scc1 .Lmy_ci_fast
	v_mov_b32_e32 v80, 0
	v_mov_b32_e32 v81, v80
	v_mov_b32_e32 v82, v80
	v_mov_b32_e32 v83, v80
	v_mov_b32_e32 v84, v80
	v_mov_b32_e32 v85, v80
	v_mov_b32_e32 v86, v80
	v_mov_b32_e32 v87, v80
	v_mov_b32_e32 v88, v80
	v_mov_b32_e32 v89, v80
	v_mov_b32_e32 v90, v80
	v_mov_b32_e32 v91, v80
	v_mov_b32_e32 v92, v80
	v_mov_b32_e32 v93, v80
	v_mov_b32_e32 v94, v80
	v_mov_b32_e32 v95, v80
	v_mov_b32_e32 v96, v80
	v_mov_b32_e32 v97, v80
	v_mov_b32_e32 v98, v80
	v_mov_b32_e32 v99, v80
	v_mov_b32_e32 v100, v80
	v_mov_b32_e32 v101, v80
	v_mov_b32_e32 v102, v80
	v_mov_b32_e32 v103, v80
	v_mov_b32_e32 v104, v80
	v_mov_b32_e32 v105, v80
	v_mov_b32_e32 v106, v80
	v_mov_b32_e32 v107, v80
	v_mov_b32_e32 v108, v80
	v_mov_b32_e32 v109, v80
	v_mov_b32_e32 v110, v80
	v_mov_b32_e32 v111, v80
	s_and_saveexec_b64 s[56:57], s[16:17]
	s_cbranch_execz .LBB0_212
	v_mov_b32_e32 v80, 0x20080
	v_mov_b32_e32 v96, 0x200c0
	v_add_u32_e32 v92, 0, v80
	s_nop 0
	ds_read_b128 v[80:83], v92
	ds_read_b128 v[84:87], v92 offset:16
	ds_read_b128 v[88:91], v92 offset:32
	ds_read_b128 v[92:95], v92 offset:48
	s_nop 0
	v_add_u32_e32 v108, 0, v96
	ds_read_b128 v[96:99], v108
	ds_read_b128 v[100:103], v108 offset:16
	ds_read_b128 v[104:107], v108 offset:32
	ds_read_b128 v[108:111], v108 offset:48
.LBB0_212:
	s_or_b64 exec, exec, s[56:57]
	v_add_u32_e32 v159, v191, v190
	v_add_u32_e32 v161, 0xffffffbf, v159
	s_waitcnt lgkmcnt(0)
	v_mfma_f32_32x32x16_bf16 v[80:95], v[140:143], v[112:115], v[80:95]
	v_mfma_f32_32x32x16_bf16 v[96:111], v[144:147], v[112:115], v[96:111]
	s_branch .Lmy_ci_join
.Lmy_ci_fast:
	v_add_u32_e32 v159, v191, v190
	v_add_u32_e32 v161, 0xffffffbf, v159
	s_waitcnt lgkmcnt(0)
	v_mfma_f32_32x32x16_bf16 v[80:95], v[140:143], v[112:115], v[220:235]
	v_mfma_f32_32x32x16_bf16 v[96:111], v[144:147], v[112:115], v[236:251]
.Lmy_ci_join:
	v_mfma_f32_32x32x16_bf16 v[80:95], v[136:139], v[116:119], v[80:95]
	v_mfma_f32_32x32x16_bf16 v[96:111], v[132:135], v[116:119], v[96:111]
	v_mfma_f32_32x32x16_bf16 v[80:95], v[128:131], v[120:123], v[80:95]
	v_mfma_f32_32x32x16_bf16 v[96:111], v[42:45], v[120:123], v[96:111]
	v_mfma_f32_32x32x16_bf16 v[80:95], v[38:41], v[124:127], v[80:95]
	v_mfma_f32_32x32x16_bf16 v[96:111], v[34:37], v[124:127], v[96:111]
	s_cmp_eq_u32 s61, 0
	s_cbranch_scc1 .Lmy_dma_mid_skip
	s_cmp_eq_u64 s[14:15], 0
	s_cbranch_scc1 .Lmy_dma_mid_skip
	v_add_u32_e32 v214, -2, v192
	v_mul_lo_u32 v214, v214, s53
	v_mov_b32_e32 v215, 0
	s_sub_i32 s32, s63, s45
	v_lshl_add_u64 v[212:213], v[154:155], 0, v[214:215]
	v_lshl_add_u64 v[216:217], v[156:157], 0, v[214:215]
	v_lshl_add_u64 v[214:215], v[212:213], 0, s[86:87]
	s_add_i32 m0, s32, 0x10000
	s_nop 0
	global_load_lds_dwordx4 v[214:215], off
	s_add_i32 m0, s32, 0x14000
	v_lshl_add_u64 v[214:215], v[212:213], 0, s[88:89]
	global_load_lds_dwordx4 v[216:217], off
	s_add_i32 m0, s32, 0x11000
	s_nop 0
	global_load_lds_dwordx4 v[214:215], off
	v_lshl_add_u64 v[214:215], v[216:217], 0, s[90:91]
	s_add_i32 m0, s32, 0x15000
	s_nop 0
	global_load_lds_dwordx4 v[214:215], off
	v_lshl_add_u64 v[214:215], v[212:213], 0, s[92:93]
	s_add_i32 m0, s32, 0x12000
	v_lshl_add_u64 v[212:213], v[212:213], 0, s[96:97]
	global_load_lds_dwordx4 v[214:215], off
	v_lshl_add_u64 v[214:215], v[216:217], 0, s[94:95]
	s_add_i32 m0, s32, 0x16000
	s_nop 0
	global_load_lds_dwordx4 v[214:215], off
	s_add_i32 m0, s32, 0x13000
	s_nop 0
	global_load_lds_dwordx4 v[212:213], off
	v_lshl_add_u64 v[212:213], v[216:217], 0, s[72:73]
	s_add_i32 m0, s32, 0x17000
	s_nop 0
	global_load_lds_dwordx4 v[212:213], off
